# P7 V-tile loop order reversed; attention next-tile K/V prefetch; P6 and P10 per-chunk vector loads hoisted to iteration top
# speedup vs baseline: 1.0301x; 1.0301x over previous
; DEVI unsigned pk2(float lo, float hi) { f32x2 v = {lo, hi}; bf16x2_t b = __builtin_convertvector(v, bf16x2_t); return __builtin_bit_cast(unsigned, b); }
; DEVI void norm1_rows(const P& p, int it) {
;     ...
;             ss2[q] += sumsq4(v[q][i]);
;             if (t[q] >= CTX) *(f32x4*)(p.out + (size_t)(b[q] * SEQ + t[q] - CTX) * 1024 + col) = v[q][i];
;         }
;         ss2[q] = wave_sum(ss2[q]);
;     }
; #pragma unroll
;     for (int q = 0; q < 2; ++q) {
;         const float rstd2 = rsqrtf(ss2[q] * (1.0f / 1024.0f) + 1e-6f);
;         const float* mod1 = mod0[q] + 9 * 3072;
;         bf16_t* hb = (bf16_t*)(p.ws + OFF_A) + (size_t)r[q] * 1024;
; #pragma unroll
;         for (int i = 0; i < 4; ++i) {
;             const int col = (i * 64 + lane) * 4;
;             const f32x4 g = *(const f32x4*)(p.g_pre1 + col), sh = *(const f32x4*)(mod1 + col), sc = *(const f32x4*)(mod1 + 1024 + col);
;             const f32x4 h = (v[q][i] * rstd2 * g) * (sc + 1.0f) + sh;
;             uint2 o; o.x = pk2(h[0], h[1]); o.y = pk2(h[2], h[3]);
;             *(uint2*)(hb + col) = o;
;         }
.LBB0_1252:
	s_or_b64 exec, exec, s[2:3]
	v_lshl_add_u64 v[78:79], v[60:61], 0, s[10:11]
	v_lshl_add_u64 v[60:61], v[60:61], 0, s[12:13]
	v_mov_b32_e32 v47, v33
	v_lshl_add_u64 v[68:69], v[60:61], 0, v[46:47]
	v_lshl_add_u64 v[72:73], v[78:79], 0, v[46:47]
	v_mov_b32_e32 v86, v25
	v_mov_b32_e32 v87, v29
	v_mov_b32_e32 v84, v24
	v_mov_b32_e32 v85, v28
	v_pk_mul_f32 v[86:87], v[86:87], v[86:87]
	v_mov_b32_e32 v88, v21
	v_mov_b32_e32 v89, v17
	v_mov_b32_e32 v82, v26
	v_mov_b32_e32 v83, v30
	v_pk_fma_f32 v[84:85], v[84:85], v[84:85], v[86:87]
	v_mov_b32_e32 v86, v20
	v_mov_b32_e32 v87, v16
	v_pk_mul_f32 v[88:89], v[88:89], v[88:89]
	v_mov_b32_e32 v80, v27
	v_mov_b32_e32 v81, v31
	v_pk_fma_f32 v[82:83], v[82:83], v[82:83], v[84:85]
	v_mov_b32_e32 v84, v22
	v_mov_b32_e32 v85, v18
	v_pk_fma_f32 v[86:87], v[86:87], v[86:87], v[88:89]
	v_pk_fma_f32 v[80:81], v[80:81], v[80:81], v[82:83]
	v_mov_b32_e32 v82, v23
	v_mov_b32_e32 v83, v19
	v_pk_fma_f32 v[84:85], v[84:85], v[84:85], v[86:87]
	v_add_f32_e32 v45, v80, v81
	v_pk_fma_f32 v[82:83], v[82:83], v[82:83], v[84:85]
	v_lshl_add_u64 v[80:81], v[42:43], 0, v[56:57]
	v_add_f32_e32 v45, v45, v82
	v_add_f32_e32 v45, v45, v83
	ds_bpermute_b32 v51, v49, v45
	s_add_i32 s21, s21, s27
	s_cmpk_gt_i32 s21, 0x10ff
	v_add_u32_e32 v44, s14, v44
	s_waitcnt lgkmcnt(0)
	v_add_f32_e32 v45, v45, v51
	ds_bpermute_b32 v51, v100, v45
	s_waitcnt lgkmcnt(0)
	v_add_f32_e32 v45, v45, v51
	ds_bpermute_b32 v51, v101, v45
	s_waitcnt lgkmcnt(0)
	v_add_f32_e32 v45, v45, v51
	ds_bpermute_b32 v51, v102, v45
	s_waitcnt lgkmcnt(0)
	v_add_f32_e32 v45, v45, v51
	ds_bpermute_b32 v51, v103, v45
	s_waitcnt lgkmcnt(0)
	v_add_f32_e32 v58, v45, v51
	ds_bpermute_b32 v76, v104, v58
	v_mov_b32_e32 v51, v33
	s_waitcnt lgkmcnt(0)
	v_pk_add_f32 v[58:59], v[58:59], v[76:77]
	s_nop 0
	v_pk_fma_f32 v[76:77], v[58:59], s[6:7], v[48:49] op_sel_hi:[1,0,0]
	v_pk_add_f32 v[56:57], v[186:187], 1.0 op_sel_hi:[1,0]
	v_mul_f32_e32 v45, 0x4b800000, v77
	v_cmp_gt_f32_e32 vcc, s20, v77
	v_pk_add_f32 v[58:59], v[184:185], 1.0 op_sel_hi:[1,0]
	s_nop 0
	v_cndmask_b32_e32 v45, v77, v45, vcc
	v_rsq_f32_e32 v45, v45
	s_nop 0
	v_mul_f32_e32 v53, 0x45800000, v45
	v_cndmask_b32_e32 v82, v45, v53, vcc
	v_pk_mul_f32 v[2:3], v[2:3], v[82:83] op_sel_hi:[1,0]
	v_pk_mul_f32 v[0:1], v[0:1], v[82:83] op_sel_hi:[1,0]
	v_pk_mul_f32 v[2:3], v[2:3], v[154:155]
	v_pk_mul_f32 v[0:1], v[0:1], v[152:153]
	v_pk_fma_f32 v[2:3], v[2:3], v[56:57], v[202:203]
	v_pk_fma_f32 v[0:1], v[0:1], v[58:59], v[200:201]
	v_lshl_add_u64 v[56:57], v[60:61], 0, v[50:51]
	v_cvt_pk_bf16_f32 v0, v0, v1
	v_cvt_pk_bf16_f32 v1, v2, v3
	global_store_dwordx2 v[80:81], v[0:1], off
	v_lshl_add_u64 v[64:65], v[78:79], 0, v[50:51]
	v_pk_mul_f32 v[10:11], v[10:11], v[82:83] op_sel_hi:[1,0]
	v_pk_mul_f32 v[8:9], v[8:9], v[82:83] op_sel_hi:[1,0]
	v_mov_b32_e32 v53, v33
	v_pk_mul_f32 v[14:15], v[14:15], v[82:83] op_sel_hi:[1,0]
	v_pk_mul_f32 v[12:13], v[12:13], v[82:83] op_sel_hi:[1,0]
	v_pk_mul_f32 v[6:7], v[6:7], v[82:83] op_sel_hi:[1,0]
	v_pk_mul_f32 v[4:5], v[4:5], v[82:83] op_sel_hi:[1,0]
	v_cmp_gt_f32_e32 vcc, s20, v76
	v_pk_mul_f32 v[0:1], v[8:9], v[156:157]
	v_pk_mul_f32 v[2:3], v[10:11], v[158:159]
	v_pk_add_f32 v[8:9], v[190:191], 1.0 op_sel_hi:[1,0]
	v_pk_add_f32 v[10:11], v[188:189], 1.0 op_sel_hi:[1,0]
	v_pk_fma_f32 v[2:3], v[2:3], v[8:9], v[206:207]
	v_pk_fma_f32 v[0:1], v[0:1], v[10:11], v[204:205]
	v_lshl_add_u64 v[8:9], v[60:61], 0, v[52:53]
	v_cvt_pk_bf16_f32 v0, v0, v1
	v_cvt_pk_bf16_f32 v1, v2, v3
	global_store_dwordx2 v[80:81], v[0:1], off offset:512
	v_lshl_add_u64 v[56:57], v[78:79], 0, v[52:53]
	v_pk_mul_f32 v[0:1], v[12:13], v[160:161]
	v_pk_mul_f32 v[2:3], v[14:15], v[162:163]
	v_pk_add_f32 v[10:11], v[194:195], 1.0 op_sel_hi:[1,0]
	v_pk_add_f32 v[8:9], v[192:193], 1.0 op_sel_hi:[1,0]
	v_lshl_add_u64 v[12:13], v[78:79], 0, v[32:33]
	v_pk_fma_f32 v[2:3], v[2:3], v[10:11], v[210:211]
	v_pk_fma_f32 v[0:1], v[0:1], v[8:9], v[208:209]
	v_lshl_add_u64 v[8:9], v[60:61], 0, v[32:33]
	v_cvt_pk_bf16_f32 v0, v0, v1
	v_cvt_pk_bf16_f32 v1, v2, v3
	global_store_dwordx2 v[80:81], v[0:1], off offset:1024
	v_lshl_add_u64 v[58:59], v[62:63], 0, s[12:13]
	v_lshl_add_u64 v[56:57], v[62:63], 0, s[10:11]
	v_pk_mul_f32 v[0:1], v[4:5], v[164:165]
	v_pk_mul_f32 v[2:3], v[6:7], v[166:167]
	v_pk_add_f32 v[4:5], v[198:199], 1.0 op_sel_hi:[1,0]
	v_pk_add_f32 v[6:7], v[196:197], 1.0 op_sel_hi:[1,0]
	v_pk_fma_f32 v[2:3], v[2:3], v[4:5], v[214:215]
	v_pk_fma_f32 v[0:1], v[0:1], v[6:7], v[212:213]
	v_lshl_add_u64 v[4:5], v[58:59], 0, v[46:47]
	v_cvt_pk_bf16_f32 v0, v0, v1
	v_cvt_pk_bf16_f32 v1, v2, v3
	global_store_dwordx2 v[80:81], v[0:1], off offset:1536
	v_lshl_add_u64 v[8:9], v[56:57], 0, v[46:47]
	v_mul_f32_e32 v12, 0x4b800000, v76
	v_cndmask_b32_e32 v12, v76, v12, vcc
	v_rsq_f32_e32 v14, v12
	v_lshl_add_u64 v[12:13], v[42:43], 0, v[54:55]
	v_mul_f32_e32 v15, 0x45800000, v14
	v_cndmask_b32_e32 v14, v14, v15, vcc
	v_pk_mul_f32 v[26:27], v[26:27], v[14:15] op_sel_hi:[1,0]
	v_pk_mul_f32 v[24:25], v[24:25], v[14:15] op_sel_hi:[1,0]
	v_pk_mul_f32 v[22:23], v[22:23], v[14:15] op_sel_hi:[1,0]
	v_pk_mul_f32 v[20:21], v[20:21], v[14:15] op_sel_hi:[1,0]
	v_pk_mul_f32 v[18:19], v[18:19], v[14:15] op_sel_hi:[1,0]
	v_pk_mul_f32 v[0:1], v[24:25], v[152:153]
	v_pk_mul_f32 v[2:3], v[26:27], v[154:155]
	v_pk_add_f32 v[6:7], v[186:187], 1.0 op_sel_hi:[1,0]
	v_pk_add_f32 v[4:5], v[184:185], 1.0 op_sel_hi:[1,0]
	v_pk_fma_f32 v[2:3], v[2:3], v[6:7], v[202:203]
	v_pk_fma_f32 v[0:1], v[0:1], v[4:5], v[200:201]
	v_lshl_add_u64 v[4:5], v[58:59], 0, v[50:51]
	v_cvt_pk_bf16_f32 v0, v0, v1
	v_cvt_pk_bf16_f32 v1, v2, v3
	global_store_dwordx2 v[12:13], v[0:1], off
; DEVI unsigned pk2(float lo, float hi) { f32x2 v = {lo, hi}; bf16x2_t b = __builtin_convertvector(v, bf16x2_t); return __builtin_bit_cast(unsigned, b); }
; DEVI float bflo(unsigned u) { return __uint_as_float(u << 16); }
; DEVI float bfhi(unsigned u) { return __uint_as_float(u & 0xffff0000u); }
; DEVI void norm1_rows(const P& p, int it) {
;     ...
;     for (int q = 0; q < 2; ++q) {
;         r[q] = it * 8 + w + 4 * q; b[q] = r[q] / TPB; t[q] = r[q] - b[q] * TPB;
;         src[q] = t[q] < CTX ? p.ctx + (size_t)(b[q] * CTX + t[q]) * 1024 : p.x + (size_t)(b[q] * SEQ + t[q] - CTX) * 1024;
;         mod0[q] = (const float*)(p.ws + OFF_MODS) + (size_t)(t[q] < CTX ? 8 : b[q]) * 3072;
;     }
;     f32x4 v[2][4], xs[2][4];
;     float ss[2] = {0.f, 0.f};
; #pragma unroll
;     for (int q = 0; q < 2; ++q) {
;         const bf16_t* y = (const bf16_t*)(p.ws + OFF_E) + (size_t)r[q] * 1024;
; #pragma unroll
;         for (int i = 0; i < 4; ++i) {
;             const uint2 q_ = *(const uint2*)(y + (i * 64 + lane) * 4);
;             v[q][i] = (f32x4){bflo(q_.x), bfhi(q_.x), bflo(q_.y), bfhi(q_.y)};
;             xs[q][i] = *(const f32x4*)(src[q] + (i * 64 + lane) * 4);
;         }
;     }
;     ...
;         for (int i = 0; i < 4; ++i) {
;             const int col = (i * 64 + lane) * 4;
;             const f32x4 g = *(const f32x4*)(p.g_pre1 + col), sh = *(const f32x4*)(mod1 + col), sc = *(const f32x4*)(mod1 + 1024 + col);
;             const f32x4 h = (v[q][i] * rstd2 * g) * (sc + 1.0f) + sh;
;             uint2 o; o.x = pk2(h[0], h[1]); o.y = pk2(h[2], h[3]);
;             *(uint2*)(hb + col) = o;
;         }
	v_lshl_add_u64 v[8:9], v[56:57], 0, v[50:51]
	v_pk_mul_f32 v[24:25], v[30:31], v[14:15] op_sel_hi:[1,0]
	v_pk_mul_f32 v[26:27], v[28:29], v[14:15] op_sel_hi:[1,0]
	v_pk_mul_f32 v[14:15], v[16:17], v[14:15] op_sel_hi:[1,0]
	v_pk_mul_f32 v[0:1], v[26:27], v[156:157]
	v_pk_mul_f32 v[2:3], v[24:25], v[158:159]
	v_pk_add_f32 v[6:7], v[190:191], 1.0 op_sel_hi:[1,0]
	v_pk_add_f32 v[4:5], v[188:189], 1.0 op_sel_hi:[1,0]
	v_pk_fma_f32 v[2:3], v[2:3], v[6:7], v[206:207]
	v_pk_fma_f32 v[0:1], v[0:1], v[4:5], v[204:205]
	v_lshl_add_u64 v[4:5], v[58:59], 0, v[52:53]
	v_cvt_pk_bf16_f32 v0, v0, v1
	v_cvt_pk_bf16_f32 v1, v2, v3
	global_store_dwordx2 v[12:13], v[0:1], off offset:512
	v_lshl_add_u64 v[8:9], v[56:57], 0, v[52:53]
	v_pk_mul_f32 v[0:1], v[20:21], v[160:161]
	v_pk_mul_f32 v[2:3], v[22:23], v[162:163]
	v_pk_add_f32 v[6:7], v[194:195], 1.0 op_sel_hi:[1,0]
	v_pk_add_f32 v[4:5], v[192:193], 1.0 op_sel_hi:[1,0]
	v_pk_fma_f32 v[2:3], v[2:3], v[6:7], v[210:211]
	v_pk_fma_f32 v[0:1], v[0:1], v[4:5], v[208:209]
	v_lshl_add_u64 v[4:5], v[58:59], 0, v[32:33]
	v_cvt_pk_bf16_f32 v0, v0, v1
	v_cvt_pk_bf16_f32 v1, v2, v3
	global_store_dwordx2 v[12:13], v[0:1], off offset:1024
	v_lshl_add_u64 v[8:9], v[56:57], 0, v[32:33]
	v_pk_mul_f32 v[0:1], v[14:15], v[164:165]
	v_pk_mul_f32 v[2:3], v[18:19], v[166:167]
	v_pk_add_f32 v[6:7], v[198:199], 1.0 op_sel_hi:[1,0]
	v_pk_add_f32 v[4:5], v[196:197], 1.0 op_sel_hi:[1,0]
	v_pk_fma_f32 v[2:3], v[2:3], v[6:7], v[214:215]
	v_pk_fma_f32 v[0:1], v[0:1], v[4:5], v[212:213]
	s_nop 0
	v_cvt_pk_bf16_f32 v0, v0, v1
	v_cvt_pk_bf16_f32 v1, v2, v3
	global_store_dwordx2 v[12:13], v[0:1], off offset:1536
	s_cbranch_scc1 .LBB0_1277
.LBB0_1253:
	v_mul_hi_i32 v0, v44, s15
	v_lshrrev_b32_e32 v1, 31, v0
	v_ashrrev_i32_e32 v0, 11, v0
	v_add_u32_e32 v9, v0, v1
	v_mul_i32_i24_e32 v6, 0xffffef00, v9
	v_mad_i32_i24 v1, v9, s16, v44
	v_lshl_add_u32 v0, v9, 12, v6
	v_cmp_gt_i32_e64 s[2:3], s7, v1
	v_cmp_lt_i32_e32 vcc, s17, v1
	v_mov_b64_e32 v[2:3], s[56:57]
	v_add3_u32 v0, v44, v0, s18
	s_and_saveexec_b64 s[4:5], vcc
	s_xor_b64 s[4:5], exec, s[4:5]
	v_mov_b64_e32 v[2:3], s[52:53]
	s_or_saveexec_b64 s[4:5], s[4:5]
	v_lshl_add_u32 v5, s21, 3, v179
	v_mov_b32_e32 v4, v0
	s_xor_b64 exec, exec, s[4:5]
	v_lshlrev_b32_e32 v4, 8, v9
	v_add3_u32 v4, v6, v5, v4
	s_or_b64 exec, exec, s[4:5]
	v_add_u32_e32 v10, 4, v44
	v_mul_hi_i32 v6, v10, s15
	v_lshrrev_b32_e32 v7, 31, v6
	v_ashrrev_i32_e32 v6, 11, v6
	v_add_u32_e32 v106, v6, v7
	v_mul_i32_i24_e32 v11, 0xffffef00, v106
	v_mad_i32_i24 v59, v106, s16, v10
	v_lshl_add_u32 v8, v106, 12, v11
	v_cmp_gt_i32_e32 vcc, s7, v59
	v_cmp_lt_i32_e64 s[4:5], s17, v59
	v_mov_b64_e32 v[6:7], s[56:57]
	v_add3_u32 v58, v44, v8, s19
	s_and_saveexec_b64 s[22:23], s[4:5]
	s_xor_b64 s[4:5], exec, s[22:23]
	v_mov_b64_e32 v[6:7], s[52:53]
	s_or_saveexec_b64 s[4:5], s[4:5]
	v_mov_b32_e32 v8, v58
	s_xor_b64 exec, exec, s[4:5]
	v_add_u32_e32 v5, v5, v11
	v_lshlrev_b32_e32 v8, 8, v106
	v_add3_u32 v8, v5, v8, 4
	s_or_b64 exec, exec, s[4:5]
	v_ashrrev_i32_e32 v11, 31, v10
	v_lshlrev_b64 v[54:55], 11, v[10:11]
	v_ashrrev_i32_e32 v45, 31, v44
	v_lshl_add_u64 v[10:11], v[40:41], 0, v[54:55]
	v_lshlrev_b64 v[56:57], 11, v[44:45]
	global_load_dwordx2 v[64:65], v[10:11], off
	global_load_dwordx2 v[66:67], v[10:11], off offset:512
	global_load_dwordx2 v[70:71], v[10:11], off offset:1024
	global_load_dwordx2 v[80:81], v[10:11], off offset:1536
	v_lshl_add_u64 v[10:11], v[40:41], 0, v[56:57]
	global_load_dwordx2 v[82:83], v[10:11], off offset:512
	global_load_dwordx2 v[84:85], v[10:11], off
	global_load_dwordx2 v[92:93], v[10:11], off offset:1536
	global_load_dwordx2 v[96:97], v[10:11], off offset:1024
	v_mul_i32_i24_e32 v10, 0xc00, v9
	v_ashrrev_i32_e32 v5, 31, v4
	v_ashrrev_i32_e32 v9, 31, v8
	v_cndmask_b32_e64 v10, v10, v105, s[2:3]
	v_lshlrev_b64 v[4:5], 12, v[4:5]
	v_lshlrev_b64 v[8:9], 12, v[8:9]
	v_ashrrev_i32_e32 v11, 31, v10
	v_mov_b32_e32 v47, v33
	v_lshl_add_u64 v[2:3], v[2:3], 0, v[4:5]
	v_lshl_add_u64 v[4:5], v[6:7], 0, v[8:9]
	v_lshl_add_u64 v[60:61], v[10:11], 2, s[0:1]
	v_lshl_add_u64 v[2:3], v[2:3], 0, v[46:47]
	v_lshl_add_u64 v[16:17], v[4:5], 0, v[46:47]
	v_lshl_add_u64 v[62:63], v[60:61], 0, s[8:9]
	global_load_dwordx4 v[108:111], v[34:35], off
	global_load_dwordx4 v[112:115], v[2:3], off
	global_load_dwordx4 v[8:11], v[2:3], off offset:1024
	global_load_dwordx4 v[12:15], v[2:3], off offset:2048
	global_load_dwordx4 v[4:7], v[2:3], off offset:3072
	global_load_dwordx4 v[24:27], v[16:17], off
	global_load_dwordx4 v[28:31], v[16:17], off offset:1024
	global_load_dwordx4 v[20:23], v[16:17], off offset:2048
	s_nop 0
	global_load_dwordx4 v[16:19], v[16:17], off offset:3072
	v_lshl_add_u64 v[2:3], v[62:63], 0, v[46:47]
	global_load_dwordx4 v[116:119], v[2:3], off
	v_lshl_add_u64 v[168:169], v[60:61], 0, v[46:47]
	v_lshl_add_u64 v[170:171], v[168:169], 0, s[8:9]
	v_lshl_add_u64 v[218:219], v[168:169], 0, s[10:11]
	v_lshl_add_u64 v[220:221], v[168:169], 0, s[12:13]
	global_load_dwordx4 v[120:123], v[34:35], off
	global_load_dwordx4 v[136:139], v[170:171], off
	global_load_dwordx4 v[124:127], v[34:35], off offset:1024
	global_load_dwordx4 v[140:143], v[170:171], off offset:1024
	global_load_dwordx4 v[128:131], v[34:35], off offset:2048
	global_load_dwordx4 v[144:147], v[170:171], off offset:2048
	global_load_dwordx4 v[132:135], v[34:35], off offset:3072
	global_load_dwordx4 v[148:151], v[170:171], off offset:3072
	global_load_dwordx4 v[152:155], v[38:39], off
	global_load_dwordx4 v[184:187], v[220:221], off
	global_load_dwordx4 v[200:203], v[218:219], off
	global_load_dwordx4 v[156:159], v[38:39], off offset:1024
	global_load_dwordx4 v[188:191], v[220:221], off offset:1024
	global_load_dwordx4 v[204:207], v[218:219], off offset:1024
	global_load_dwordx4 v[160:163], v[38:39], off offset:2048
	global_load_dwordx4 v[192:195], v[220:221], off offset:2048
	global_load_dwordx4 v[208:211], v[218:219], off offset:2048
	global_load_dwordx4 v[164:167], v[38:39], off offset:3072
	global_load_dwordx4 v[196:199], v[220:221], off offset:3072
	global_load_dwordx4 v[212:215], v[218:219], off offset:3072
	v_cmp_lt_i32_e64 s[2:3], s17, v1
	v_ashrrev_i32_e32 v1, 31, v0
	s_waitcnt vmcnt(37)
; DEVI void norm1_rows(const P& p, int it) {
;     ...
; #pragma unroll
;     for (int q = 0; q < 2; ++q) {
; #pragma unroll
;         for (int i = 0; i < 4; ++i) ss[q] += sumsq4(v[q][i]);
;         ss[q] = wave_sum(ss[q]);
;     }
;     float ss2[2] = {0.f, 0.f};
; #pragma unroll
;     for (int q = 0; q < 2; ++q) {
;         const float rstd = rsqrtf(ss[q] * (1.0f / 1024.0f) + 1e-6f);
; #pragma unroll
;         for (int i = 0; i < 4; ++i) {
;             const int col = (i * 64 + lane) * 4;
;             const f32x4 g = *(const f32x4*)(p.g_post0 + col), gt = *(const f32x4*)(mod0[q] + 2048 + col);
;             v[q][i] = xs[q][i] + gt * (v[q][i] * rstd * g);
;             ss2[q] += sumsq4(v[q][i]);
;             if (t[q] >= CTX) *(f32x4*)(p.out + (size_t)(b[q] * SEQ + t[q] - CTX) * 1024 + col) = v[q][i];
;         }
;         ss2[q] = wave_sum(ss2[q]);
;     }
	v_lshlrev_b32_e32 v78, 16, v64
	v_and_b32_e32 v79, 0xffff0000, v64
	s_waitcnt vmcnt(33)
	v_and_b32_e32 v89, 0xffff0000, v82
	s_waitcnt vmcnt(32)
	v_and_b32_e32 v88, 0xffff0000, v84
	v_lshlrev_b32_e32 v76, 16, v65
	v_and_b32_e32 v77, 0xffff0000, v65
	v_lshlrev_b32_e32 v72, 16, v66
	v_and_b32_e32 v73, 0xffff0000, v66
	v_lshlrev_b32_e32 v74, 16, v67
	v_and_b32_e32 v75, 0xffff0000, v67
	v_lshlrev_b32_e32 v64, 16, v80
	v_and_b32_e32 v65, 0xffff0000, v80
	v_lshlrev_b32_e32 v66, 16, v81
	v_and_b32_e32 v67, 0xffff0000, v81
	v_lshlrev_b32_e32 v91, 16, v82
	v_lshlrev_b32_e32 v90, 16, v84
	s_waitcnt vmcnt(31)
	v_and_b32_e32 v81, 0xffff0000, v92
	s_waitcnt vmcnt(30)
	v_and_b32_e32 v80, 0xffff0000, v96
	v_pk_mul_f32 v[2:3], v[88:89], v[88:89]
	v_lshlrev_b32_e32 v99, 16, v83
	v_lshlrev_b32_e32 v98, 16, v85
	v_and_b32_e32 v95, 0xffff0000, v83
	v_and_b32_e32 v94, 0xffff0000, v85
	v_lshlrev_b32_e32 v83, 16, v92
	v_lshlrev_b32_e32 v82, 16, v96
	v_lshlrev_b32_e32 v87, 16, v93
	v_and_b32_e32 v85, 0xffff0000, v93
	v_pk_mul_f32 v[92:93], v[80:81], v[80:81]
	v_pk_fma_f32 v[2:3], v[90:91], v[90:91], v[2:3]
	v_lshlrev_b32_e32 v86, 16, v97
	v_pk_fma_f32 v[92:93], v[82:83], v[82:83], v[92:93]
	v_pk_fma_f32 v[2:3], v[98:99], v[98:99], v[2:3]
	v_and_b32_e32 v84, 0xffff0000, v97
	v_pk_fma_f32 v[92:93], v[86:87], v[86:87], v[92:93]
	v_pk_fma_f32 v[2:3], v[94:95], v[94:95], v[2:3]
	v_pk_fma_f32 v[92:93], v[84:85], v[84:85], v[92:93]
	v_add_f32_e32 v2, v2, v3
	v_add_f32_e32 v2, v2, v92
	v_add_f32_e32 v2, v2, v93
	ds_bpermute_b32 v3, v49, v2
	v_mul_f32_e32 v45, v79, v79
	v_mul_f32_e32 v47, v73, v73
	v_fmac_f32_e32 v45, v78, v78
	v_fmac_f32_e32 v47, v72, v72
	s_waitcnt lgkmcnt(0)
	v_add_f32_e32 v2, v2, v3
	v_and_b32_e32 v69, 0xffff0000, v70
	v_fmac_f32_e32 v45, v76, v76
	v_fmac_f32_e32 v47, v74, v74
	ds_bpermute_b32 v3, v100, v2
	v_lshlrev_b32_e32 v68, 16, v70
	v_mul_f32_e32 v51, v69, v69
	v_fmac_f32_e32 v45, v77, v77
	v_fmac_f32_e32 v47, v75, v75
	v_lshlrev_b32_e32 v70, 16, v71
	v_fmac_f32_e32 v51, v68, v68
	v_add_f32_e32 v45, v45, v47
	v_mul_f32_e32 v47, v65, v65
	v_and_b32_e32 v71, 0xffff0000, v71
	v_fmac_f32_e32 v51, v70, v70
	v_fmac_f32_e32 v47, v64, v64
	v_fmac_f32_e32 v51, v71, v71
	v_fmac_f32_e32 v47, v66, v66
	v_add_f32_e32 v45, v45, v51
	v_fmac_f32_e32 v47, v67, v67
	s_waitcnt lgkmcnt(0)
	v_add_f32_e32 v2, v2, v3
	v_add_f32_e32 v45, v45, v47
	ds_bpermute_b32 v3, v101, v2
	ds_bpermute_b32 v47, v49, v45
	v_lshlrev_b64 v[92:93], 12, v[0:1]
	v_mov_b32_e32 v0, v98
	v_lshl_add_u64 v[92:93], v[36:37], 0, v[92:93]
	s_waitcnt lgkmcnt(1)
	v_add_f32_e32 v2, v2, v3
	s_waitcnt lgkmcnt(0)
	v_add_f32_e32 v45, v45, v47
	ds_bpermute_b32 v3, v102, v2
	ds_bpermute_b32 v47, v100, v45
	s_waitcnt lgkmcnt(1)
	v_add_f32_e32 v2, v2, v3
	s_waitcnt lgkmcnt(0)
	v_add_f32_e32 v45, v45, v47
	ds_bpermute_b32 v3, v103, v2
	ds_bpermute_b32 v47, v101, v45
	s_waitcnt lgkmcnt(1)
	v_add_f32_e32 v2, v2, v3
	s_waitcnt lgkmcnt(0)
	v_add_f32_e32 v45, v45, v47
	ds_bpermute_b32 v3, v104, v2
	ds_bpermute_b32 v47, v102, v45
	s_waitcnt lgkmcnt(1)
	v_add_f32_e32 v1, v2, v3
	s_waitcnt lgkmcnt(0)
	v_add_f32_e32 v45, v45, v47
	v_fmamk_f32 v1, v1, 0x3a800000, v48
	ds_bpermute_b32 v47, v103, v45
	v_mul_f32_e32 v2, 0x4b800000, v1
	v_cmp_gt_f32_e64 s[4:5], s20, v1
	s_waitcnt lgkmcnt(0)
	v_add_f32_e32 v45, v45, v47
	v_cndmask_b32_e64 v1, v1, v2, s[4:5]
	v_rsq_f32_e32 v2, v1
	ds_bpermute_b32 v107, v104, v45
	v_mov_b32_e32 v1, v94
	v_mul_f32_e32 v3, 0x45800000, v2
	v_cndmask_b32_e64 v96, v2, v3, s[4:5]
	v_mov_b32_e32 v2, v90
	v_mov_b32_e32 v3, v88
	v_pk_mul_f32 v[0:1], v[96:97], v[0:1] op_sel_hi:[0,1]
	v_pk_mul_f32 v[2:3], v[96:97], v[2:3] op_sel_hi:[0,1]
	s_waitcnt vmcnt(29)
	v_pk_mul_f32 v[108:109], v[108:109], v[2:3]
	v_pk_mul_f32 v[0:1], v[110:111], v[0:1]
	s_waitcnt vmcnt(0)
	v_pk_fma_f32 v[2:3], v[118:119], v[0:1], v[114:115]
	v_pk_fma_f32 v[0:1], v[116:117], v[108:109], v[112:113]
	s_and_saveexec_b64 s[4:5], s[2:3]
	s_cbranch_execz .LBB0_1263
	global_store_dwordx4 v[92:93], v[0:3], off
.LBB0_1263:
	s_or_b64 exec, exec, s[4:5]
	v_mov_b32_e32 v51, v33
	v_lshl_add_u64 v[112:113], v[62:63], 0, v[50:51]
	v_mov_b32_e32 v97, v96
	v_mov_b32_e32 v94, v99
	v_mov_b32_e32 v98, v96
	v_mov_b32_e32 v99, v96
	v_mov_b32_e32 v88, v91
	v_pk_mul_f32 v[90:91], v[98:99], v[94:95]
	v_pk_mul_f32 v[88:89], v[96:97], v[88:89]
	v_pk_mul_f32 v[90:91], v[90:91], v[126:127]
	v_pk_mul_f32 v[88:89], v[88:89], v[124:125]
	v_pk_fma_f32 v[10:11], v[142:143], v[90:91], v[10:11]
	v_pk_fma_f32 v[8:9], v[140:141], v[88:89], v[8:9]
	s_and_saveexec_b64 s[4:5], s[2:3]
	s_cbranch_execz .LBB0_1265
	global_store_dwordx4 v[92:93], v[8:11], off offset:1024
; DEVI void norm1_rows(const P& p, int it) {
;     ...
; #pragma unroll
;     for (int q = 0; q < 2; ++q) {
;         const float rstd = rsqrtf(ss[q] * (1.0f / 1024.0f) + 1e-6f);
; #pragma unroll
;         for (int i = 0; i < 4; ++i) {
;             const int col = (i * 64 + lane) * 4;
;             const f32x4 g = *(const f32x4*)(p.g_post0 + col), gt = *(const f32x4*)(mod0[q] + 2048 + col);
;             v[q][i] = xs[q][i] + gt * (v[q][i] * rstd * g);
;             ss2[q] += sumsq4(v[q][i]);
;             if (t[q] >= CTX) *(f32x4*)(p.out + (size_t)(b[q] * SEQ + t[q] - CTX) * 1024 + col) = v[q][i];
;         }
;         ss2[q] = wave_sum(ss2[q]);
;     }
.LBB0_1265:
	s_or_b64 exec, exec, s[4:5]
	v_mov_b32_e32 v53, v33
	v_lshl_add_u64 v[94:95], v[62:63], 0, v[52:53]
	v_mov_b32_e32 v94, v86
	v_mov_b32_e32 v95, v84
	v_mov_b32_e32 v112, v82
	v_mov_b32_e32 v113, v80
	v_pk_mul_f32 v[94:95], v[98:99], v[94:95]
	v_pk_mul_f32 v[98:99], v[96:97], v[112:113]
	v_pk_mul_f32 v[90:91], v[94:95], v[130:131]
	v_pk_mul_f32 v[88:89], v[98:99], v[128:129]
	v_pk_fma_f32 v[14:15], v[146:147], v[90:91], v[14:15]
	v_pk_fma_f32 v[12:13], v[144:145], v[88:89], v[12:13]
	s_and_saveexec_b64 s[4:5], s[2:3]
	s_cbranch_execz .LBB0_1267
	global_store_dwordx4 v[92:93], v[12:15], off offset:2048
.LBB0_1267:
	s_or_b64 exec, exec, s[4:5]
	v_lshl_add_u64 v[62:63], v[62:63], 0, v[32:33]
	v_mov_b32_e32 v84, v87
	v_mov_b32_e32 v62, v96
	v_mov_b32_e32 v63, v96
	v_mov_b32_e32 v80, v83
	v_pk_mul_f32 v[62:63], v[62:63], v[84:85]
	v_pk_mul_f32 v[80:81], v[96:97], v[80:81]
	v_pk_mul_f32 v[62:63], v[62:63], v[134:135]
	v_pk_mul_f32 v[80:81], v[80:81], v[132:133]
	v_pk_fma_f32 v[6:7], v[150:151], v[62:63], v[6:7]
	v_pk_fma_f32 v[4:5], v[148:149], v[80:81], v[4:5]
	s_and_saveexec_b64 s[4:5], s[2:3]
	s_cbranch_execz .LBB0_1269
	global_store_dwordx4 v[92:93], v[4:7], off offset:3072
.LBB0_1269:
	s_or_b64 exec, exec, s[4:5]
	v_mul_i32_i24_e32 v47, 0xc00, v106
	v_cndmask_b32_e32 v62, v47, v105, vcc
	v_ashrrev_i32_e32 v63, 31, v62
	v_lshl_add_u64 v[62:63], v[62:63], 2, s[0:1]
	v_lshl_add_u64 v[80:81], v[62:63], 0, s[8:9]
	v_mov_b32_e32 v47, v33
	v_lshl_add_u64 v[82:83], v[80:81], 0, v[46:47]
	v_mul_f32_e32 v47, v1, v1
	v_mul_f32_e32 v51, v9, v9
	v_mul_f32_e32 v53, v13, v13
	v_fmac_f32_e32 v47, v0, v0
	v_fmac_f32_e32 v51, v8, v8
	v_mul_f32_e32 v82, v5, v5
	v_fmac_f32_e32 v53, v12, v12
	v_fmac_f32_e32 v47, v2, v2
	v_fmac_f32_e32 v51, v10, v10
	v_fmac_f32_e32 v82, v4, v4
	v_fmac_f32_e32 v53, v14, v14
	v_fmac_f32_e32 v47, v3, v3
	v_fmac_f32_e32 v51, v11, v11
	v_fmac_f32_e32 v82, v6, v6
	v_fmac_f32_e32 v53, v15, v15
	v_add_f32_e32 v47, v47, v51
	v_fmac_f32_e32 v82, v7, v7
	v_add_f32_e32 v47, v47, v53
	v_add_f32_e32 v47, v47, v82
	ds_bpermute_b32 v51, v49, v47
	s_waitcnt lgkmcnt(1)
	v_add_f32_e32 v45, v45, v107
	v_fmamk_f32 v45, v45, 0x3a800000, v48
	v_mul_f32_e32 v53, 0x4b800000, v45
	v_cmp_gt_f32_e64 s[2:3], s20, v45
	s_waitcnt lgkmcnt(0)
	v_add_f32_e32 v47, v47, v51
	ds_bpermute_b32 v51, v100, v47
	v_cndmask_b32_e64 v45, v45, v53, s[2:3]
	v_rsq_f32_e32 v45, v45
	v_cmp_lt_i32_e32 vcc, s17, v59
	v_ashrrev_i32_e32 v59, 31, v58
	s_waitcnt lgkmcnt(0)
	v_add_f32_e32 v47, v47, v51
	ds_bpermute_b32 v51, v101, v47
	v_mul_f32_e32 v53, 0x45800000, v45
	v_lshlrev_b64 v[92:93], 12, v[58:59]
	v_cndmask_b32_e64 v82, v45, v53, s[2:3]
	v_pk_mul_f32 v[94:95], v[82:83], v[76:77] op_sel_hi:[0,1]
	s_waitcnt lgkmcnt(0)
	v_add_f32_e32 v47, v47, v51
	ds_bpermute_b32 v51, v102, v47
	v_pk_mul_f32 v[78:79], v[82:83], v[78:79] op_sel_hi:[0,1]
	s_waitcnt lgkmcnt(0)
	v_add_f32_e32 v47, v47, v51
	ds_bpermute_b32 v51, v103, v47
	s_waitcnt lgkmcnt(0)
	v_add_f32_e32 v59, v47, v51
	ds_bpermute_b32 v77, v104, v59
	v_pk_mul_f32 v[86:87], v[94:95], v[122:123]
	v_pk_mul_f32 v[78:79], v[78:79], v[120:121]
	v_pk_fma_f32 v[26:27], v[138:139], v[86:87], v[26:27]
	v_pk_fma_f32 v[24:25], v[136:137], v[78:79], v[24:25]
	v_lshl_add_u64 v[78:79], v[36:37], 0, v[92:93]
	s_and_saveexec_b64 s[2:3], vcc
	s_cbranch_execz .LBB0_1271
	global_store_dwordx4 v[78:79], v[24:27], off
.LBB0_1271:
	s_or_b64 exec, exec, s[2:3]
	v_mov_b32_e32 v51, v33
	v_lshl_add_u64 v[84:85], v[80:81], 0, v[50:51]
	v_mov_b32_e32 v83, v82
	v_mov_b32_e32 v84, v82
	v_mov_b32_e32 v85, v82
	v_pk_mul_f32 v[74:75], v[84:85], v[74:75]
	v_pk_mul_f32 v[72:73], v[82:83], v[72:73]
	v_pk_mul_f32 v[74:75], v[74:75], v[126:127]
	v_pk_mul_f32 v[72:73], v[72:73], v[124:125]
	v_pk_fma_f32 v[30:31], v[142:143], v[74:75], v[30:31]
	v_pk_fma_f32 v[28:29], v[140:141], v[72:73], v[28:29]
	s_and_saveexec_b64 s[2:3], vcc
	s_cbranch_execz .LBB0_1273
	global_store_dwordx4 v[78:79], v[28:31], off offset:1024
.LBB0_1273:
	s_or_b64 exec, exec, s[2:3]
	v_mov_b32_e32 v53, v33
	v_lshl_add_u64 v[86:87], v[80:81], 0, v[52:53]
	v_pk_mul_f32 v[70:71], v[84:85], v[70:71]
	v_pk_mul_f32 v[68:69], v[82:83], v[68:69]
	v_pk_mul_f32 v[70:71], v[70:71], v[130:131]
	v_pk_mul_f32 v[68:69], v[68:69], v[128:129]
	v_pk_fma_f32 v[22:23], v[146:147], v[70:71], v[22:23]
	v_pk_fma_f32 v[20:21], v[144:145], v[68:69], v[20:21]
	s_and_saveexec_b64 s[2:3], vcc
	s_cbranch_execz .LBB0_1275
	global_store_dwordx4 v[78:79], v[20:23], off offset:2048
.LBB0_1275:
	s_or_b64 exec, exec, s[2:3]
	v_lshl_add_u64 v[72:73], v[80:81], 0, v[32:33]
	v_mov_b32_e32 v80, v82
	v_mov_b32_e32 v81, v82
	v_pk_mul_f32 v[64:65], v[82:83], v[64:65]
	v_pk_mul_f32 v[66:67], v[80:81], v[66:67]
	v_pk_mul_f32 v[64:65], v[64:65], v[132:133]
	v_pk_mul_f32 v[66:67], v[66:67], v[134:135]
	v_pk_fma_f32 v[16:17], v[148:149], v[64:65], v[16:17]
	v_pk_fma_f32 v[18:19], v[150:151], v[66:67], v[18:19]
	s_and_saveexec_b64 s[2:3], vcc
	s_cbranch_execz .LBB0_1252
	global_store_dwordx4 v[78:79], v[16:19], off offset:3072
	s_branch .LBB0_1252

; __global__ void __launch_bounds__(256, 2) fwd_megakernel(P p) {
;     ...
;         EpiG2B eb{(bf16_t*)(ws + OFF_D + 17 * MiB)};
;         for (int L = bid; L < 272 * 2; L += G) {
;             int pm, pn; tile_map(L, 272, 2, pm, pn);
;             gemm_tile<false>(bufA + (size_t)pm * 128 * 1024, bufA, 1 << 30, 1024, W1T + (size_t)(2304 + pn * 128) * 1024, 1024, 16, smem, eb, pm * 128, pn * 128);
;         }
.LBB0_1369:
	s_add_u32 s0, s90, 0xdd00000
	s_addc_u32 s1, s91, 0
	s_sub_i32 s36, s27, s86
	s_add_i32 s36, s36, -1
	s_cmpk_gt_i32 s36, 0x21f
	s_cbranch_scc1 .LBB0_1374
	s_mov_b32 s3, 0
	s_mov_b64 s[4:5], 0x10000
	s_mov_b64 s[6:7], 0x20000
	s_mov_b64 s[8:9], 0x30000
	s_mov_b64 s[10:11], 0x80
	s_mov_b64 s[12:13], 0x10080
	s_mov_b64 s[14:15], 0x20080
	s_mov_b64 s[16:17], 0x30080
	s_mov_b64 s[18:19], 0x1a600080
	s_mov_b64 s[20:21], 0x1a610080
	s_mov_b64 s[22:23], 0x1a620080
	s_mov_b64 s[24:25], 0x1a630080
	s_mov_b32 s33, 0x78787879
	s_movk_i32 s34, 0xef00
	s_movk_i32 s35, 0x2200
	v_mov_b32_e32 v65, 0

; DEVI void attn_item(const P& p, int item, char* smem) {
;     ...
;     for (int mh = 0; mh < 2; ++mh) {
;         const int mo = mh * 32;
;         bf16x8 Qf[2][2];
; #pragma unroll
;         for (int m = 0; m < 2; ++m)
; #pragma unroll
;             for (int kk = 0; kk < 2; ++kk) Qf[m][kk] = *(const bf16x8*)(Q + (size_t)(mo + 16 * m + fr) * 1024 + kk * 32 + fq * 8);
;         f32x4 O[4][2];
; #pragma unroll
;         for (int nd = 0; nd < 4; ++nd)
; #pragma unroll
;             for (int m = 0; m < 2; ++m) O[nd][m] = (f32x4){0.f, 0.f, 0.f, 0.f};
;         float mrow[2], lrow[2];
; #pragma unroll
;         for (int m = 0; m < 2; ++m) { mrow[m] = sinkv; lrow[m] = (fq == 0) ? 1.0f : 0.0f; }
;         for (int ti = 0; ti < 9; ++ti) {
.LBB0_1432:
	v_or_b32_e32 v0, s4, v174
	v_lshlrev_b32_e32 v122, 10, v0
	v_lshlrev_b32_e32 v0, 11, v0
	v_or_b32_e32 v120, 0x4000, v122
	v_lshl_add_u64 v[2:3], v[108:109], 0, v[0:1]
	v_lshlrev_b32_e32 v0, 1, v120
	global_load_dwordx4 v[22:25], v[2:3], off
	global_load_dwordx4 v[26:29], v[2:3], off offset:64
	v_lshl_add_u64 v[2:3], v[108:109], 0, v[0:1]
	global_load_dwordx4 v[30:33], v[2:3], off
	global_load_dwordx4 v[34:37], v[2:3], off offset:64
	v_mov_b32_e32 v2, v1
	v_mov_b32_e32 v3, v1
	v_mov_b32_e32 v0, v1
	v_mov_b64_e32 v[40:41], v[2:3]
	v_mov_b64_e32 v[16:17], v[2:3]
	v_mov_b64_e32 v[44:45], v[2:3]
	v_mov_b64_e32 v[12:13], v[2:3]
	v_mov_b64_e32 v[48:49], v[2:3]
	v_mov_b64_e32 v[8:9], v[2:3]
	v_mov_b64_e32 v[20:21], v[2:3]
	v_add_u32_e32 v140, s4, v137
	v_mov_b64_e32 v[38:39], v[0:1]
	v_mov_b64_e32 v[14:15], v[0:1]
	v_mov_b64_e32 v[42:43], v[0:1]
	v_mov_b64_e32 v[10:11], v[0:1]
	v_mov_b64_e32 v[46:47], v[0:1]
	v_mov_b64_e32 v[6:7], v[0:1]
	v_mov_b64_e32 v[18:19], v[0:1]
	v_mov_b64_e32 v[4:5], v[2:3]
	s_xor_b64 s[0:1], s[2:3], -1
	v_add_u32_e32 v141, 16, v140
	v_add_u32_e32 v142, -2, v140
	v_add_u32_e32 v143, -3, v140
	v_add_u32_e32 v144, -16, v140
	v_subrev_u32_e32 v145, 17, v140
	v_subrev_u32_e32 v146, 18, v140
	v_subrev_u32_e32 v147, 19, v140
	v_subrev_u32_e32 v148, 32, v140
	v_subrev_u32_e32 v149, 33, v140
	v_subrev_u32_e32 v150, 34, v140
	v_subrev_u32_e32 v151, 35, v140
	v_subrev_u32_e32 v152, 48, v140
	v_subrev_u32_e32 v153, 49, v140
	v_subrev_u32_e32 v154, 50, v140
	v_subrev_u32_e32 v155, 51, v140
	v_add_u32_e32 v156, 14, v140
	v_add_u32_e32 v157, 13, v140
	s_mov_b32 s28, 0
	s_mov_b32 s99, 0
	s_mov_b32 s47, s43
	v_mov_b32_e32 v158, v121
	v_mov_b32_e32 v139, v121
	v_mov_b32_e32 v160, v138
	v_mov_b32_e32 v159, v138
	v_mov_b64_e32 v[2:3], v[0:1]
	s_branch .LBB0_1435

; DEVI void attn_item(const P& p, int item, char* smem) {
;     ...
;             int tok0; bool lat;
;             if (ti < 5) { const int kb = q0 - 128 + 64 * ti; if (kb < 0 || kb >= SEQ) continue; tok0 = CTX + kb; lat = true; }
;             else { tok0 = (ti - 5) * 64; lat = false; }
;             __syncthreads();
; #pragma unroll
;             for (int i = 0; i < 2; ++i) {
;                 const int row = (tid >> 3) + 32 * i, ch = tid & 7;
;                 const uint4 kv = *(const uint4*)(KB + ((size_t)(b * TPB + tok0 + row)) * 256 + kvh * 64 + ch * 8);
;                 *(uint4*)(sK + row * 128 + ((ch ^ (row & 7)) << 4)) = kv;
;                 const uint4 vv = *(const uint4*)(VT + ((size_t)(b * 256 + kvh * 64 + row)) * TPB + tok0 + ch * 8);
;                 *(uint4*)(sV + row * 128 + ((ch ^ ((row >> 1) & 7)) << 4)) = vv;
;             }
;             __syncthreads();
;             bf16x8 Kf[4][2];
; #pragma unroll
;             for (int n = 0; n < 4; ++n)
; #pragma unroll
;                 for (int kk = 0; kk < 2; ++kk) Kf[n][kk] = *(const bf16x8*)(sK + (16 * n + fr) * 128 + (((kk * 4 + fq) ^ (fr & 7)) << 4));
;             bf16x8 Pf[2][2];
; #pragma unroll
;             for (int m = 0; m < 2; ++m) {
;                 f32x4 s[4];
; #pragma unroll
;                 for (int n = 0; n < 4; ++n) {
;                     s[n] = (f32x4){0.f, 0.f, 0.f, 0.f};
; #pragma unroll
;                     for (int kk = 0; kk < 2; ++kk) s[n] = __builtin_amdgcn_mfma_f32_16x16x32_bf16(Kf[n][kk], Qf[m][kk], s[n], 0, 0, 0);
.LBB0_1439:
	s_andn2_b64 vcc, exec, s[4:5]
	s_cbranch_vccnz .LBB0_1434
	s_ashr_i32 s31, s30, 31
	s_cmp_lg_u32 s99, 0
	s_cbranch_scc1 .Lat_have
	s_add_i32 s4, s30, s46
	v_add_u32_e32 v50, s4, v216
	v_add_u32_e32 v60, s4, v128
	v_ashrrev_i32_e32 v51, 31, v50
	v_ashrrev_i32_e32 v61, 31, v60
	v_lshl_add_u64 v[58:59], s[30:31], 1, v[100:101]
	v_lshlrev_b64 v[50:51], 9, v[50:51]
	v_lshlrev_b64 v[60:61], 9, v[60:61]
	v_lshl_add_u64 v[50:51], v[112:113], 0, v[50:51]
	v_lshl_add_u64 v[54:55], v[58:59], 0, v[114:115]
	v_lshl_add_u64 v[60:61], v[112:113], 0, v[60:61]
	v_lshl_add_u64 v[62:63], v[58:59], 0, v[116:117]
	global_load_dwordx4 v[190:193], v[50:51], off
	global_load_dwordx4 v[194:197], v[54:55], off
	global_load_dwordx4 v[198:201], v[60:61], off
	global_load_dwordx4 v[202:205], v[62:63], off
.Lat_have:
	s_barrier
	v_add_u32_e32 v66, v123, v127
	v_add_u32_e32 v67, v124, v127
	v_add_u32_e32 v68, v123, v129
	v_add_u32_e32 v69, v124, v129
	s_and_b32 s4, s28, 11
	s_cmp_eq_u32 s4, 0
	s_cselect_b64 s[18:19], -1, 0
	s_and_b64 s[18:19], s[2:3], s[18:19]
	v_sub_u32_e32 v0, s30, v140
	v_subrev_u32_e32 v171, s30, v142
	v_subrev_u32_e32 v170, s30, v143
	v_subrev_u32_e32 v168, s30, v144
	v_subrev_u32_e32 v169, s30, v145
	v_subrev_u32_e32 v165, s30, v146
	v_subrev_u32_e32 v162, s30, v147
	v_subrev_u32_e32 v166, s30, v148
	v_subrev_u32_e32 v163, s30, v149
	v_subrev_u32_e32 v167, s30, v150
	v_subrev_u32_e32 v164, s30, v151
	v_subrev_u32_e32 v161, s30, v140
	v_cmp_gt_u32_e64 s[4:5], s38, v0
	v_cmp_lt_u32_e64 s[6:7], s39, v171
	v_cmp_lt_u32_e64 s[8:9], s39, v170
	v_cmp_lt_u32_e64 s[10:11], s39, v168
	v_cmp_lt_u32_e64 s[12:13], s39, v169
	v_cmp_lt_u32_e64 s[14:15], s39, v165
	v_cmp_lt_u32_e64 s[16:17], s39, v162
	s_andn2_b64 vcc, exec, s[18:19]
	v_cmp_lt_u32_e64 s[20:21], s39, v163
	v_cmp_lt_u32_e64 s[22:23], s39, v167
	v_cmp_lt_u32_e64 s[24:25], s39, v164
	s_waitcnt vmcnt(0)
	ds_write_b128 v66, v[190:193]
	ds_write_b128 v67, v[194:197] offset:8192
	ds_write_b128 v68, v[198:201]
	ds_write_b128 v69, v[202:205] offset:8192
	s_mov_b32 s99, 0
	s_cmp_lt_u32 s28, 8
	s_cbranch_scc0 .Lat_nopf
	s_cmp_gt_u32 s28, 3
	s_cbranch_scc1 .Lat_ctx
	s_add_i32 s100, s47, 64
	s_add_i32 s98, s100, 0xffffff00
	s_cmpk_lt_u32 s98, 0x1000
	s_cbranch_scc0 .Lat_nopf
	s_branch .Lat_issue
.Lat_ctx:
	s_lshl_b32 s100, s28, 6
	s_add_i32 s100, s100, 0xffffff00
.Lat_issue:
	s_mov_b32 s101, 0
	s_add_i32 s98, s100, s46
	v_add_u32_e32 v50, s98, v216
	v_add_u32_e32 v60, s98, v128
	v_ashrrev_i32_e32 v51, 31, v50
	v_ashrrev_i32_e32 v61, 31, v60
	v_lshl_add_u64 v[58:59], s[100:101], 1, v[100:101]
	v_lshlrev_b64 v[50:51], 9, v[50:51]
	v_lshlrev_b64 v[60:61], 9, v[60:61]
	v_lshl_add_u64 v[50:51], v[112:113], 0, v[50:51]
	v_lshl_add_u64 v[54:55], v[58:59], 0, v[114:115]
	v_lshl_add_u64 v[60:61], v[112:113], 0, v[60:61]
	v_lshl_add_u64 v[62:63], v[58:59], 0, v[116:117]
	global_load_dwordx4 v[190:193], v[50:51], off
	global_load_dwordx4 v[194:197], v[54:55], off
	global_load_dwordx4 v[198:201], v[60:61], off
	global_load_dwordx4 v[202:205], v[62:63], off
	s_mov_b32 s99, 1
.Lat_nopf:
	s_waitcnt lgkmcnt(0)
	s_barrier
	ds_read_b128 v[70:73], v130
	ds_read_b128 v[62:65], v130 offset:2048
	ds_read_b128 v[54:57], v130 offset:4096
	ds_read_b128 v[82:85], v130 offset:6144
	ds_read_b128 v[94:97], v131
	ds_read_b128 v[90:93], v131 offset:2048
	ds_read_b128 v[86:89], v131 offset:4096
	ds_read_b128 v[66:69], v131 offset:6144
	s_waitcnt lgkmcnt(7)
	v_mfma_f32_16x16x32_bf16 v[50:53], v[70:73], v[22:25], 0
	s_waitcnt lgkmcnt(6)
	v_mfma_f32_16x16x32_bf16 v[58:61], v[62:65], v[22:25], 0
	s_waitcnt lgkmcnt(5)
	v_mfma_f32_16x16x32_bf16 v[182:185], v[54:57], v[22:25], 0
	s_waitcnt lgkmcnt(4)
	v_mfma_f32_16x16x32_bf16 v[186:189], v[82:85], v[22:25], 0
	s_waitcnt lgkmcnt(3)
	v_mfma_f32_16x16x32_bf16 v[78:81], v[94:97], v[26:29], v[50:53]
	s_nop 2
	v_cndmask_b32_e64 v50, 0, 1, s[18:19]
	s_waitcnt lgkmcnt(2)
	v_mfma_f32_16x16x32_bf16 v[74:77], v[90:93], v[26:29], v[58:61]
	v_cmp_ne_u32_e64 s[2:3], 1, v50
	v_cmp_lt_u32_e64 s[18:19], s39, v166
	s_waitcnt lgkmcnt(1)
	v_mfma_f32_16x16x32_bf16 v[58:61], v[86:89], v[26:29], v[182:185]
	s_waitcnt lgkmcnt(0)
	v_mfma_f32_16x16x32_bf16 v[50:53], v[66:69], v[26:29], v[186:189]
	s_cbranch_vccnz .LBB0_1442
	v_cmp_gt_u32_e32 vcc, s37, v161
	v_subrev_u32_e32 v173, s30, v152
	v_cndmask_b32_e64 v79, v136, v79, s[4:5]
	v_cndmask_b32_e32 v78, v78, v136, vcc
	v_cmp_lt_u32_e32 vcc, s39, v173
	v_subrev_u32_e32 v173, s30, v153
	v_cndmask_b32_e64 v80, v136, v80, s[6:7]
	v_cndmask_b32_e32 v50, v136, v50, vcc
	v_cmp_lt_u32_e32 vcc, s39, v173
	v_subrev_u32_e32 v173, s30, v154
	v_cndmask_b32_e64 v81, v136, v81, s[8:9]
	v_cndmask_b32_e32 v51, v136, v51, vcc
	v_cmp_lt_u32_e32 vcc, s39, v173
	v_subrev_u32_e32 v173, s30, v155
	v_cndmask_b32_e64 v74, v136, v74, s[10:11]
	v_cndmask_b32_e32 v52, v136, v52, vcc
	v_cmp_lt_u32_e32 vcc, s39, v173
	v_cndmask_b32_e64 v75, v136, v75, s[12:13]
	v_cndmask_b32_e64 v76, v136, v76, s[14:15]
	v_cndmask_b32_e64 v77, v136, v77, s[16:17]
	v_cndmask_b32_e64 v58, v136, v58, s[18:19]
	v_cndmask_b32_e64 v59, v136, v59, s[20:21]
	v_cndmask_b32_e64 v60, v136, v60, s[22:23]
	v_cndmask_b32_e64 v61, v136, v61, s[24:25]
	v_cndmask_b32_e32 v53, v136, v53, vcc

; DEVI float bflo(unsigned u) { return __uint_as_float(u << 16); }
; DEVI float bfhi(unsigned u) { return __uint_as_float(u & 0xffff0000u); }
; DEVI void final_rows(const P& p, int it) {
;     const int lane = threadIdx.x & 63, w = threadIdx.x >> 6;
;     f32x4 v[2][4], xs[2][4];
;     float ss[2] = {0.f, 0.f};
; #pragma unroll
;     for (int q = 0; q < 2; ++q) {
;         const int r = it * 8 + w + 4 * q;
;         const bf16_t* y = (const bf16_t*)(p.ws + OFF_E) + (size_t)r * 1024;
;         const float* o = p.out + (size_t)r * 1024;
; #pragma unroll
;         for (int i = 0; i < 4; ++i) {
;             const uint2 q_ = *(const uint2*)(y + (i * 64 + lane) * 4);
;             v[q][i] = (f32x4){bflo(q_.x), bfhi(q_.x), bflo(q_.y), bfhi(q_.y)};
;             xs[q][i] = *(const f32x4*)(o + (i * 64 + lane) * 4);
;         }
;     }
; #pragma unroll
;     for (int q = 0; q < 2; ++q) {
; #pragma unroll
;         for (int i = 0; i < 4; ++i) ss[q] += sumsq4(v[q][i]);
;         ss[q] = wave_sum(ss[q]);
.LBB0_1558:
	s_or_b64 exec, exec, s[0:1]
	s_cmpk_gt_i32 s86, 0xfff
	s_barrier
	s_cbranch_scc1 .LBB0_1561
	v_mbcnt_hi_u32_b32 v0, -1, v181
	v_and_b32_e32 v2, 64, v0
	v_add_u32_e32 v2, 64, v2
	v_xor_b32_e32 v3, 32, v0
	v_cmp_lt_i32_e32 vcc, v3, v2
	v_and_b32_e32 v10, 0xfc, v176
	v_mov_b32_e32 v1, 0
	v_cndmask_b32_e32 v3, v0, v3, vcc
	v_lshlrev_b32_e32 v17, 2, v3
	v_xor_b32_e32 v3, 16, v0
	v_cmp_lt_i32_e32 vcc, v3, v2
	v_or_b32_e32 v12, 0x100, v10
	v_or_b32_e32 v14, 0x200, v10
	v_cndmask_b32_e32 v3, v0, v3, vcc
	v_lshlrev_b32_e32 v38, 2, v3
	v_xor_b32_e32 v3, 8, v0
	v_cmp_lt_i32_e32 vcc, v3, v2
	v_or_b32_e32 v16, 0x300, v10
	v_lshlrev_b32_e32 v4, 1, v10
	v_cndmask_b32_e32 v3, v0, v3, vcc
	v_lshlrev_b32_e32 v39, 2, v3
	v_xor_b32_e32 v3, 4, v0
	v_cmp_lt_i32_e32 vcc, v3, v2
	v_mov_b32_e32 v5, v1
	v_lshl_add_u64 v[4:5], s[40:41], 0, v[4:5]
	v_cndmask_b32_e32 v3, v0, v3, vcc
	v_lshlrev_b32_e32 v40, 2, v3
	v_xor_b32_e32 v3, 2, v0
	v_cmp_lt_i32_e32 vcc, v3, v2
	v_lshl_add_u32 v8, s86, 3, v179
	s_lshl_b32 s3, s27, 3
	v_cndmask_b32_e32 v3, v0, v3, vcc
	v_lshlrev_b32_e32 v41, 2, v3
	v_xor_b32_e32 v3, 1, v0
	v_cmp_lt_i32_e32 vcc, v3, v2
	s_mov_b64 s[0:1], 0x1ef02000
	v_mov_b32_e32 v11, v1
	v_cndmask_b32_e32 v0, v0, v3, vcc
	v_lshlrev_b32_e32 v42, 2, v0
	v_lshlrev_b32_e32 v0, 2, v10
	v_lshl_add_u64 v[2:3], s[48:49], 0, v[0:1]
	v_lshl_add_u64 v[6:7], s[88:89], 0, v[0:1]
	v_lshlrev_b32_e32 v0, 2, v10
	v_lshlrev_b32_e32 v10, 2, v12
	v_lshlrev_b32_e32 v12, 2, v14
	v_mov_b32_e32 v13, v1
	v_lshlrev_b32_e32 v14, 2, v16
	v_mov_b32_e32 v15, v1
	s_mov_b32 s2, 0x3a800000
	v_mov_b32_e32 v16, 0x358637bd
	s_mov_b32 s4, 0x800000
	s_mov_b64 s[6:7], 0x4000
.LBB0_1560:
	v_ashrrev_i32_e32 v9, 31, v8
	v_lshlrev_b64 v[18:19], 11, v[8:9]
	v_add_u32_e32 v26, 4, v8
	v_lshl_add_u64 v[18:19], v[4:5], 0, v[18:19]
	v_ashrrev_i32_e32 v27, 31, v26
	global_load_dwordx2 v[20:21], v[18:19], off offset:512
	global_load_dwordx2 v[22:23], v[18:19], off
	global_load_dwordx2 v[24:25], v[18:19], off offset:1536
	global_load_dwordx2 v[28:29], v[18:19], off offset:1024
	v_lshlrev_b64 v[18:19], 11, v[26:27]
	v_lshl_add_u64 v[18:19], v[4:5], 0, v[18:19]
	global_load_dwordx2 v[32:33], v[18:19], off offset:512
	global_load_dwordx2 v[56:57], v[18:19], off
	global_load_dwordx2 v[58:59], v[18:19], off offset:1536
	global_load_dwordx2 v[60:61], v[18:19], off offset:1024
	v_ashrrev_i32_e32 v30, 12, v8
	v_lshlrev_b64 v[18:19], 12, v[8:9]
	v_add_u32_e32 v9, 9, v30
	v_lshl_add_u64 v[36:37], v[6:7], 0, v[18:19]
	v_mul_hi_i32_i24_e32 v19, 0x3000, v9
	v_mul_i32_i24_e32 v18, 0x3000, v9
	v_lshl_add_u64 v[18:19], s[90:91], 0, v[18:19]
	v_lshl_add_u64 v[62:63], v[18:19], 0, s[0:1]
	global_load_dwordx4 v[44:47], v[2:3], off
	v_lshl_add_u64 v[18:19], v[62:63], 0, v[0:1]
	global_load_dwordx4 v[48:51], v[36:37], off
	global_load_dwordx4 v[52:55], v[18:19], off
	v_lshl_add_u64 v[86:87], v[62:63], 0, v[0:1]
	v_lshl_add_u64 v[148:149], v[36:37], 0, s[6:7]
	global_load_dwordx4 v[88:91], v[2:3], off
	global_load_dwordx4 v[104:107], v[86:87], off
	global_load_dwordx4 v[132:135], v[148:149], off
	global_load_dwordx4 v[92:95], v[2:3], off offset:1024
	global_load_dwordx4 v[108:111], v[86:87], off offset:1024
	global_load_dwordx4 v[120:123], v[36:37], off offset:1024
	global_load_dwordx4 v[136:139], v[148:149], off offset:1024
	global_load_dwordx4 v[96:99], v[2:3], off offset:2048
	global_load_dwordx4 v[112:115], v[86:87], off offset:2048
	global_load_dwordx4 v[124:127], v[36:37], off offset:2048
	global_load_dwordx4 v[140:143], v[148:149], off offset:2048
	global_load_dwordx4 v[100:103], v[2:3], off offset:3072
	global_load_dwordx4 v[116:119], v[86:87], off offset:3072
	global_load_dwordx4 v[128:131], v[36:37], off offset:3072
	global_load_dwordx4 v[144:147], v[148:149], off offset:3072
	s_add_i32 s86, s86, s27
	s_cmpk_gt_i32 s86, 0xfff
	v_add_u32_e32 v8, s3, v8
	s_waitcnt vmcnt(25)
	v_and_b32_e32 v67, 0xffff0000, v20
	s_waitcnt vmcnt(24)
	v_and_b32_e32 v66, 0xffff0000, v22
	v_lshlrev_b32_e32 v65, 16, v20
	s_waitcnt vmcnt(22)
	v_lshlrev_b32_e32 v72, 16, v28
	v_and_b32_e32 v74, 0xffff0000, v28
	v_lshlrev_b32_e32 v76, 16, v29
	v_and_b32_e32 v78, 0xffff0000, v29
	s_waitcnt vmcnt(21)
	v_and_b32_e32 v29, 0xffff0000, v32
	s_waitcnt vmcnt(20)
	v_and_b32_e32 v28, 0xffff0000, v56
	v_lshlrev_b32_e32 v64, 16, v22
	v_lshlrev_b32_e32 v73, 16, v24
	v_and_b32_e32 v75, 0xffff0000, v24
	v_pk_mul_f32 v[80:81], v[66:67], v[66:67]
	v_lshlrev_b32_e32 v31, 16, v32
	v_lshlrev_b32_e32 v30, 16, v56
	s_waitcnt vmcnt(18)
	v_lshlrev_b32_e32 v20, 16, v60
	v_and_b32_e32 v19, 0xffff0000, v58
	v_and_b32_e32 v18, 0xffff0000, v60
	v_lshlrev_b32_e32 v24, 16, v61
	v_and_b32_e32 v22, 0xffff0000, v61
	v_pk_mul_f32 v[60:61], v[28:29], v[28:29]
	v_lshlrev_b32_e32 v69, 16, v21
	v_lshlrev_b32_e32 v68, 16, v23
	v_and_b32_e32 v71, 0xffff0000, v21
	v_pk_mul_f32 v[82:83], v[74:75], v[74:75]
	v_lshlrev_b32_e32 v35, 16, v33
	v_lshlrev_b32_e32 v34, 16, v57
	v_and_b32_e32 v32, 0xffff0000, v57
	v_lshlrev_b32_e32 v21, 16, v58
	v_pk_fma_f32 v[56:57], v[64:65], v[64:65], v[80:81]
	v_pk_mul_f32 v[80:81], v[18:19], v[18:19]
	v_pk_fma_f32 v[60:61], v[30:31], v[30:31], v[60:61]
	v_and_b32_e32 v70, 0xffff0000, v23
	v_lshlrev_b32_e32 v77, 16, v25
	v_and_b32_e32 v79, 0xffff0000, v25
	v_and_b32_e32 v33, 0xffff0000, v33
	v_lshlrev_b32_e32 v25, 16, v59
	v_and_b32_e32 v23, 0xffff0000, v59
	v_pk_fma_f32 v[58:59], v[72:73], v[72:73], v[82:83]
	v_pk_fma_f32 v[56:57], v[68:69], v[68:69], v[56:57]
	v_pk_fma_f32 v[80:81], v[20:21], v[20:21], v[80:81]
	v_pk_fma_f32 v[60:61], v[34:35], v[34:35], v[60:61]
	v_pk_fma_f32 v[58:59], v[76:77], v[76:77], v[58:59]
	v_pk_fma_f32 v[56:57], v[70:71], v[70:71], v[56:57]
	v_pk_fma_f32 v[80:81], v[24:25], v[24:25], v[80:81]
	v_pk_fma_f32 v[60:61], v[32:33], v[32:33], v[60:61]
	v_pk_fma_f32 v[58:59], v[78:79], v[78:79], v[58:59]
	v_pk_fma_f32 v[80:81], v[22:23], v[22:23], v[80:81]
	v_mov_b32_e32 v83, v56
	v_mov_b32_e32 v82, v60
	v_mov_b32_e32 v56, v61
	v_mov_b32_e32 v85, v58
	v_mov_b32_e32 v84, v80
	v_pk_add_f32 v[56:57], v[82:83], v[56:57]
	v_mov_b32_e32 v58, v81
	v_pk_add_f32 v[56:57], v[56:57], v[84:85]
	v_mov_b32_e32 v82, v68
	v_pk_add_f32 v[56:57], v[56:57], v[58:59]
	ds_bpermute_b32 v59, v17, v57
	ds_bpermute_b32 v58, v17, v56
	v_mov_b32_e32 v83, v70
	v_mov_b32_e32 v70, v69
	v_mov_b32_e32 v68, v76
	v_mov_b32_e32 v69, v78
	s_waitcnt lgkmcnt(0)
; DEVI void final_rows(const P& p, int it) {
;     ...
; #pragma unroll
;     for (int q = 0; q < 2; ++q) {
; #pragma unroll
;         for (int i = 0; i < 4; ++i) ss[q] += sumsq4(v[q][i]);
;         ss[q] = wave_sum(ss[q]);
;     }
; #pragma unroll
;     for (int q = 0; q < 2; ++q) {
;         const int r = it * 8 + w + 4 * q, b = r >> 12;
;         const float* mod1 = (const float*)(p.ws + OFF_MODS) + (size_t)(9 + b) * 3072;
;         float* o = p.out + (size_t)r * 1024;
;         const float rstd = rsqrtf(ss[q] * (1.0f / 1024.0f) + 1e-6f);
; #pragma unroll
;         for (int i = 0; i < 4; ++i) {
;             const int col = (i * 64 + lane) * 4;
;             const f32x4 g = *(const f32x4*)(p.g_post1 + col), gt = *(const f32x4*)(mod1 + 2048 + col);
;             *(f32x4*)(o + col) = xs[q][i] + gt * (v[q][i] * rstd * g);
;         }
;     }
	v_pk_add_f32 v[56:57], v[56:57], v[58:59]
	ds_bpermute_b32 v59, v38, v57
	ds_bpermute_b32 v58, v38, v56
	v_mov_b32_e32 v78, v77
	s_waitcnt lgkmcnt(0)
	v_pk_add_f32 v[56:57], v[56:57], v[58:59]
	ds_bpermute_b32 v59, v39, v57
	ds_bpermute_b32 v58, v39, v56
	s_waitcnt lgkmcnt(0)
	v_pk_add_f32 v[56:57], v[56:57], v[58:59]
	ds_bpermute_b32 v59, v40, v57
	ds_bpermute_b32 v58, v40, v56
	s_waitcnt lgkmcnt(0)
	v_pk_add_f32 v[56:57], v[56:57], v[58:59]
	ds_bpermute_b32 v59, v41, v57
	ds_bpermute_b32 v58, v41, v56
	s_waitcnt lgkmcnt(0)
	v_pk_add_f32 v[60:61], v[56:57], v[58:59]
	ds_bpermute_b32 v81, v42, v61
	ds_bpermute_b32 v80, v42, v60
	s_waitcnt lgkmcnt(0)
	v_pk_add_f32 v[60:61], v[60:61], v[80:81]
	s_nop 0
	v_pk_fma_f32 v[60:61], v[60:61], s[2:3], v[16:17] op_sel_hi:[1,0,0]
	v_mov_b32_e32 v80, v64
	v_mul_f32_e32 v9, 0x4b800000, v61
	v_cmp_gt_f32_e32 vcc, s4, v61
	v_mov_b32_e32 v81, v66
	v_mov_b32_e32 v66, v65
	v_cndmask_b32_e32 v9, v61, v9, vcc
	v_rsq_f32_e32 v9, v9
	s_nop 0
	v_mul_f32_e32 v43, 0x45800000, v9
	v_cndmask_b32_e32 v64, v9, v43, vcc
	v_pk_mul_f32 v[82:83], v[64:65], v[82:83] op_sel_hi:[0,1]
	v_pk_mul_f32 v[80:81], v[64:65], v[80:81] op_sel_hi:[0,1]
	s_waitcnt vmcnt(0)
	v_pk_mul_f32 v[44:45], v[44:45], v[80:81]
	v_pk_mul_f32 v[46:47], v[46:47], v[82:83]
	v_pk_fma_f32 v[44:45], v[52:53], v[44:45], v[48:49]
	v_pk_fma_f32 v[46:47], v[54:55], v[46:47], v[50:51]
	global_store_dwordx4 v[36:37], v[44:47], off
	v_lshl_add_u64 v[48:49], v[62:63], 0, v[10:11]
	v_pk_mul_f32 v[52:53], v[64:65], v[66:67] op_sel_hi:[0,1]
	v_pk_mul_f32 v[54:55], v[64:65], v[70:71] op_sel_hi:[0,1]
	v_lshl_add_u64 v[80:81], v[62:63], 0, v[12:13]
	v_mov_b32_e32 v66, v72
	v_mov_b32_e32 v67, v74
	v_pk_mul_f32 v[66:67], v[64:65], v[66:67] op_sel_hi:[0,1]
	v_pk_mul_f32 v[68:69], v[64:65], v[68:69] op_sel_hi:[0,1]
	v_ashrrev_i32_e32 v9, 12, v26
	v_mov_b32_e32 v74, v73
	v_lshlrev_b64 v[26:27], 12, v[26:27]
	v_add_u32_e32 v9, 9, v9
	v_cmp_gt_f32_e32 vcc, s4, v60
	v_pk_mul_f32 v[46:47], v[94:95], v[54:55]
	v_pk_mul_f32 v[44:45], v[92:93], v[52:53]
	v_pk_fma_f32 v[46:47], v[110:111], v[46:47], v[122:123]
	v_pk_fma_f32 v[44:45], v[108:109], v[44:45], v[120:121]
	global_store_dwordx4 v[36:37], v[44:47], off offset:1024
	s_nop 0
	s_nop 0
	v_pk_mul_f32 v[46:47], v[68:69], v[98:99]
	v_pk_mul_f32 v[44:45], v[66:67], v[96:97]
	v_pk_fma_f32 v[46:47], v[114:115], v[46:47], v[126:127]
	v_pk_fma_f32 v[44:45], v[112:113], v[44:45], v[124:125]
	global_store_dwordx4 v[36:37], v[44:47], off offset:2048
	v_lshl_add_u64 v[48:49], v[62:63], 0, v[14:15]
	v_pk_mul_f32 v[52:53], v[64:65], v[74:75] op_sel_hi:[0,1]
	v_pk_mul_f32 v[54:55], v[64:65], v[78:79] op_sel_hi:[0,1]
	v_lshl_add_u64 v[62:63], v[6:7], 0, v[26:27]
	v_mul_hi_i32_i24_e32 v27, 0x3000, v9
	v_mul_i32_i24_e32 v26, 0x3000, v9
	v_lshl_add_u64 v[26:27], s[90:91], 0, v[26:27]
	v_lshl_add_u64 v[66:67], v[26:27], 0, s[0:1]
	v_lshl_add_u64 v[26:27], v[66:67], 0, v[0:1]
	v_mul_f32_e32 v9, 0x4b800000, v60
	v_cndmask_b32_e32 v9, v60, v9, vcc
	v_rsq_f32_e32 v9, v9
	v_pk_mul_f32 v[46:47], v[54:55], v[102:103]
	v_pk_mul_f32 v[44:45], v[52:53], v[100:101]
	v_pk_fma_f32 v[46:47], v[118:119], v[46:47], v[130:131]
	v_pk_fma_f32 v[44:45], v[116:117], v[44:45], v[128:129]
	global_store_dwordx4 v[36:37], v[44:47], off offset:3072
	s_nop 0
	v_mov_b32_e32 v27, v28
	v_mul_f32_e32 v28, 0x45800000, v9
	v_mov_b32_e32 v26, v30
	v_mov_b32_e32 v36, v34
	v_mov_b32_e32 v37, v32
	v_cndmask_b32_e32 v60, v9, v28, vcc
	v_pk_mul_f32 v[26:27], v[60:61], v[26:27] op_sel_hi:[0,1]
	v_pk_mul_f32 v[36:37], v[60:61], v[36:37] op_sel_hi:[0,1]
	v_mov_b32_e32 v28, v31
	v_mov_b32_e32 v32, v35
	v_pk_mul_f32 v[36:37], v[36:37], v[90:91]
	v_pk_mul_f32 v[26:27], v[26:27], v[88:89]
	v_pk_fma_f32 v[46:47], v[106:107], v[36:37], v[134:135]
	v_pk_fma_f32 v[44:45], v[104:105], v[26:27], v[132:133]
	global_store_dwordx4 v[62:63], v[44:47], off
	v_lshl_add_u64 v[26:27], v[66:67], 0, v[10:11]
	v_pk_mul_f32 v[26:27], v[60:61], v[28:29] op_sel_hi:[0,1]
	v_pk_mul_f32 v[28:29], v[60:61], v[32:33] op_sel_hi:[0,1]
	v_lshl_add_u64 v[52:53], v[66:67], 0, v[12:13]
	v_pk_mul_f32 v[28:29], v[28:29], v[94:95]
	v_pk_mul_f32 v[26:27], v[26:27], v[92:93]
	v_pk_fma_f32 v[28:29], v[110:111], v[28:29], v[138:139]
	v_pk_fma_f32 v[26:27], v[108:109], v[26:27], v[136:137]
	global_store_dwordx4 v[62:63], v[26:29], off offset:1024
	s_nop 0
	v_mov_b32_e32 v48, v20
	v_mov_b32_e32 v49, v18
	v_mov_b32_e32 v50, v24
	v_mov_b32_e32 v51, v22
	v_pk_mul_f32 v[48:49], v[60:61], v[48:49] op_sel_hi:[0,1]
	v_pk_mul_f32 v[50:51], v[60:61], v[50:51] op_sel_hi:[0,1]
	v_mov_b32_e32 v18, v21
	v_mov_b32_e32 v22, v25
	v_pk_mul_f32 v[18:19], v[60:61], v[18:19] op_sel_hi:[0,1]
	v_pk_mul_f32 v[20:21], v[60:61], v[22:23] op_sel_hi:[0,1]
	v_pk_mul_f32 v[28:29], v[50:51], v[98:99]
	v_pk_mul_f32 v[26:27], v[48:49], v[96:97]
	v_pk_fma_f32 v[28:29], v[114:115], v[28:29], v[142:143]
	v_pk_fma_f32 v[26:27], v[112:113], v[26:27], v[140:141]
	global_store_dwordx4 v[62:63], v[26:29], off offset:2048
	v_lshl_add_u64 v[30:31], v[66:67], 0, v[14:15]
	v_pk_mul_f32 v[20:21], v[20:21], v[102:103]
	v_pk_mul_f32 v[18:19], v[18:19], v[100:101]
	v_pk_fma_f32 v[20:21], v[118:119], v[20:21], v[146:147]
	v_pk_fma_f32 v[18:19], v[116:117], v[18:19], v[144:145]
	global_store_dwordx4 v[62:63], v[18:21], off offset:3072
	s_cbranch_scc0 .LBB0_1560

; __global__ void __launch_bounds__(256, 2) fwd_megakernel(P p) {
;     cg::grid_group cgrid = cg::this_grid();
;     extern __shared__ __attribute__((aligned(16))) char smem[];
	.amdhsa_kernel _Z14fwd_megakernel1P
		.amdhsa_group_segment_fixed_size 0
		.amdhsa_private_segment_fixed_size 0
		.amdhsa_kernarg_size 480
		.amdhsa_user_sgpr_count 2
		.amdhsa_user_sgpr_dispatch_ptr 0
		.amdhsa_user_sgpr_queue_ptr 0
		.amdhsa_user_sgpr_kernarg_segment_ptr 1
		.amdhsa_user_sgpr_dispatch_id 0
		.amdhsa_user_sgpr_kernarg_preload_length 0
		.amdhsa_user_sgpr_kernarg_preload_offset 0
		.amdhsa_user_sgpr_private_segment_size 0
		.amdhsa_uses_dynamic_stack 0
		.amdhsa_enable_private_segment 0
		.amdhsa_system_sgpr_workgroup_id_x 1
		.amdhsa_system_sgpr_workgroup_id_y 0
		.amdhsa_system_sgpr_workgroup_id_z 0
		.amdhsa_system_sgpr_workgroup_info 0
		.amdhsa_system_vgpr_workitem_id 2
		.amdhsa_next_free_vgpr 231
		.amdhsa_next_free_sgpr 102
		.amdhsa_accum_offset 232
		.amdhsa_reserve_vcc 1
		.amdhsa_float_round_mode_32 0
		.amdhsa_float_round_mode_16_64 0
		.amdhsa_float_denorm_mode_32 3
		.amdhsa_float_denorm_mode_16_64 3
		.amdhsa_dx10_clamp 1
		.amdhsa_ieee_mode 1
		.amdhsa_fp16_overflow 0
		.amdhsa_tg_split 0
		.amdhsa_exception_fp_ieee_invalid_op 0
		.amdhsa_exception_fp_denorm_src 0
		.amdhsa_exception_fp_ieee_div_zero 0
		.amdhsa_exception_fp_ieee_overflow 0
		.amdhsa_exception_fp_ieee_underflow 0
		.amdhsa_exception_fp_ieee_inexact 0
		.amdhsa_exception_int_div_zero 0
	.end_amdhsa_kernel

; __global__ void __launch_bounds__(256, 2) fwd_megakernel(P p) {
;     cg::grid_group cgrid = cg::this_grid();
;     extern __shared__ __attribute__((aligned(16))) char smem[];
amdhsa.kernels:
  - .agpr_count:     0
    .args:
      - .offset:         0
        .size:           224
        .value_kind:     by_value
      - .offset:         224
        .size:           4
        .value_kind:     hidden_block_count_x
      - .offset:         228
        .size:           4
        .value_kind:     hidden_block_count_y
      - .offset:         232
        .size:           4
        .value_kind:     hidden_block_count_z
      - .offset:         236
        .size:           2
        .value_kind:     hidden_group_size_x
      - .offset:         238
        .size:           2
        .value_kind:     hidden_group_size_y
      - .offset:         240
        .size:           2
        .value_kind:     hidden_group_size_z
      - .offset:         242
        .size:           2
        .value_kind:     hidden_remainder_x
      - .offset:         244
        .size:           2
        .value_kind:     hidden_remainder_y
      - .offset:         246
        .size:           2
        .value_kind:     hidden_remainder_z
      - .offset:         264
        .size:           8
        .value_kind:     hidden_global_offset_x
      - .offset:         272
        .size:           8
        .value_kind:     hidden_global_offset_y
      - .offset:         280
        .size:           8
        .value_kind:     hidden_global_offset_z
      - .offset:         288
        .size:           2
        .value_kind:     hidden_grid_dims
      - .offset:         312
        .size:           8
        .value_kind:     hidden_multigrid_sync_arg
      - .offset:         344
        .size:           4
        .value_kind:     hidden_dynamic_lds_size
    .group_segment_fixed_size: 0
    .kernarg_segment_align: 8
    .kernarg_segment_size: 480
    .language:       OpenCL C
    .language_version:
      - 2
      - 0
    .max_flat_workgroup_size: 256
    .name:           _Z14fwd_megakernel1P
    .private_segment_fixed_size: 0
    .sgpr_count:     108
    .sgpr_spill_count: 46
    .symbol:         _Z14fwd_megakernel1P.kd
    .uniform_work_group_size: 1
    .uses_dynamic_stack: false
    .vgpr_count:     231
    .vgpr_spill_count: 0
    .wavefront_size: 64
